# v143 + bpermute address computation interleaved with the product chains, all three total-A bpermutes issued early
# speedup vs baseline: 1.0027x; 1.0027x over previous
; __device__ __forceinline__ void attn_unit(LAS unsigned char* lds, const bf16_t* Qm, const bf16_t* Km, const bf16_t* VT, const bf16_t* GBm, bf16_t* YB, int b, int hp, int qb) {
;     ...
;             const int qi = qw + fr;
;             float be[2][8], om[2][8];
; #pragma unroll
;             for (int c = 0; c < 2; ++c)
; #pragma unroll
;                 for (int i = 0; i < 8; ++i) {
;                     const float z = s[2 * c + (i >> 2)][i & 3];
;                     const int key = k0 + 32 * c + 8 * fq + i;
;                     const float e = __builtin_amdgcn_exp2f(-fabsf(z));
;                     const float r = __builtin_amdgcn_rcpf(1.0f + e);
;                     const bool pos = z >= 0.f, valid = key < qi;
;                     be[c][i] = valid ? (pos ? r : e * r) : 0.f;
;                     om[c][i] = valid ? (pos ? e * r : r) : 1.f;
;                 }
;             float suf[2][8], Gs[2], Tt[2];
; #pragma unroll
;             for (int c = 0; c < 2; ++c) {
;                 float run = 1.f;
; #pragma unroll
;                 for (int i = 7; i >= 0; --i) { suf[c][i] = run; run *= om[c][i]; }
;                 const float t1 = __shfl(run, (lane + 16) & 63), t2 = __shfl(run, (lane + 32) & 63), t3 = __shfl(run, (lane + 48) & 63);
;                 Gs[c] = (fq < 3 ? t1 : 1.f) * (fq < 2 ? t2 : 1.f) * (fq < 1 ? t3 : 1.f);
;                 Tt[c] = (run * t1) * (t2 * t3);
;             }
.Lattn_nomask:
	ds_read_b128 v[120:123], v116
	ds_read_b128 v[124:127], v116 offset:64
	ds_read_b128 v[128:131], v116 offset:1088
	ds_read_b128 v[132:135], v116 offset:1152
	s_waitcnt lgkmcnt(3)
	v_mfma_f32_16x16x32_bf16 v[120:123], v[120:123], v[0:3], 0
	s_waitcnt lgkmcnt(2)
	v_mfma_f32_16x16x32_bf16 v[120:123], v[124:127], v[4:7], v[120:123]
	ds_read_b128 v[124:127], v116 offset:128
	ds_read_b128 v[136:139], v116 offset:192
	s_waitcnt lgkmcnt(3)
	v_mfma_f32_16x16x32_bf16 v[128:131], v[128:131], v[0:3], 0
	s_waitcnt lgkmcnt(1)
	v_mfma_f32_16x16x32_bf16 v[120:123], v[124:127], v[8:11], v[120:123]
	ds_read_b128 v[124:127], v116 offset:1216
	ds_read_b128 v[140:143], v116 offset:1280
	ds_read_b128 v[144:147], v116 offset:8704
	ds_read_b128 v[148:151], v116 offset:8768
	v_mfma_f32_16x16x32_bf16 v[128:131], v[132:135], v[4:7], v[128:131]
	ds_read_b128 v[132:135], v116 offset:8832
	ds_read_b128 v[152:155], v116 offset:8896
	ds_read_b128 v[156:159], v116 offset:9792
	ds_read_b128 v[160:163], v116 offset:9856
	s_waitcnt lgkmcnt(8)
	v_mfma_f32_16x16x32_bf16 v[120:123], v[136:139], v[12:15], v[120:123]
	ds_read_b128 v[136:139], v116 offset:9920
	ds_read_b128 v[164:167], v116 offset:9984
	s_waitcnt lgkmcnt(9)
	v_mfma_f32_16x16x32_bf16 v[124:127], v[124:127], v[8:11], v[128:131]
	s_nop 3
	v_exp_f32_e32 v97, v120
	s_nop 0
	v_add_f32_e32 v101, 1.0, v97
	s_waitcnt lgkmcnt(7)
	v_mfma_f32_16x16x32_bf16 v[128:131], v[144:147], v[0:3], 0
	v_rcp_f32_e32 v168, v101
	s_nop 0
	v_mul_f32_e32 v101, v97, v168
	s_waitcnt lgkmcnt(6)
	v_mfma_f32_16x16x32_bf16 v[128:131], v[148:151], v[4:7], v[128:131]
	v_mfma_f32_16x16x32_bf16 v[124:127], v[140:143], v[12:15], v[124:127]
	v_exp_f32_e32 v142, v121
	v_exp_f32_e32 v143, v122
	s_waitcnt lgkmcnt(5)
	v_mfma_f32_16x16x32_bf16 v[128:131], v[132:135], v[8:11], v[128:131]
	v_add_f32_e32 v103, 1.0, v142
	v_rcp_f32_e32 v103, v103
	s_waitcnt lgkmcnt(3)
	v_mfma_f32_16x16x32_bf16 v[132:135], v[156:159], v[0:3], 0
	v_add_f32_e32 v120, 1.0, v143
	v_rcp_f32_e32 v120, v120
	s_waitcnt lgkmcnt(2)
	v_mfma_f32_16x16x32_bf16 v[132:135], v[160:163], v[4:7], v[132:135]
	s_waitcnt lgkmcnt(1)
	v_mfma_f32_16x16x32_bf16 v[132:135], v[136:139], v[8:11], v[132:135]
	v_exp_f32_e32 v144, v123
	v_exp_f32_e32 v145, v124
	v_add_f32_e32 v121, 1.0, v144
	v_rcp_f32_e32 v121, v121
	v_add_f32_e32 v122, 1.0, v145
	v_rcp_f32_e32 v122, v122
	v_mfma_f32_16x16x32_bf16 v[128:131], v[152:155], v[12:15], v[128:131]
	s_nop 0
	s_nop 0
	v_exp_f32_e32 v146, v125
	s_nop 0
	v_add_f32_e32 v123, 1.0, v146
	v_rcp_f32_e32 v123, v123
	s_nop 0
	s_nop 0
	v_exp_f32_e32 v138, v128
	v_exp_f32_e32 v131, v131
	v_exp_f32_e32 v126, v126
	s_nop 0
	v_add_f32_e32 v124, 1.0, v126
	v_rcp_f32_e32 v124, v124
	s_waitcnt lgkmcnt(0)
	v_mfma_f32_16x16x32_bf16 v[132:135], v[164:167], v[12:15], v[132:135]
	v_exp_f32_e32 v127, v127
	s_nop 0
	v_add_f32_e32 v125, 1.0, v127
	v_rcp_f32_e32 v147, v125
	v_add_f32_e32 v136, 1.0, v138
	v_rcp_f32_e32 v140, v136
	v_exp_f32_e32 v129, v129
	v_exp_f32_e32 v130, v130
	v_mul_f32_e32 v128, v138, v140
	v_add_f32_e32 v125, 1.0, v129
	v_add_f32_e32 v136, 1.0, v130
	v_add_f32_e32 v137, 1.0, v131
	v_rcp_f32_e32 v125, v125
	v_rcp_f32_e32 v141, v136
	v_rcp_f32_e32 v148, v137
	v_mul_f32_e32 v153, v147, v124
	v_mul_f32_e32 v154, v123, v153
	v_mul_f32_e32 v155, v122, v154
	v_exp_f32_e32 v132, v132
	v_exp_f32_e32 v133, v133
	v_exp_f32_e32 v134, v134
	v_exp_f32_e32 v99, v135
	v_mul_f32_e32 v156, v121, v155
	v_add_f32_e32 v136, 1.0, v132
	v_add_f32_e32 v137, 1.0, v133
	v_add_f32_e32 v138, 1.0, v134
	v_add_f32_e32 v139, 1.0, v99
	v_rcp_f32_e32 v149, v136
	v_rcp_f32_e32 v150, v137
	v_rcp_f32_e32 v152, v138
	v_rcp_f32_e32 v151, v139
	v_mul_f32_e32 v157, v120, v156
	v_mul_f32_e32 v103, v103, v157
	v_or_b32_e32 v135, v105, v107
	v_mul_f32_e32 v136, v168, v103
	v_lshlrev_b32_e32 v135, 2, v135
	v_mul_f32_e32 v152, v151, v152
	v_xor_b32_e32 v135, 0x80, v135
	ds_bpermute_b32 v138, v118, v136
	v_mul_f32_e32 v150, v150, v152
	ds_bpermute_b32 v137, v135, v136
	ds_bpermute_b32 v139, v119, v136
	v_mul_f32_e32 v149, v149, v150
	v_mul_f32_e32 v148, v148, v149
	v_mul_f32_e32 v158, v141, v148
	v_mul_f32_e32 v159, v125, v158
	s_waitcnt lgkmcnt(2)
	v_cndmask_b32_e64 v97, 1.0, v137, s[10:11]
	s_waitcnt lgkmcnt(1)
; #define LAS __attribute__((address_space(3)))
; __device__ __forceinline__ unsigned cvt_pk_bf16(float lo, float hi) { unsigned r; asm volatile("v_cvt_pk_bf16_f32 %0, %1, %2" : "=v"(r) : "v"(lo), "v"(hi)); return r; }
; __device__ __forceinline__ void attn_unit(LAS unsigned char* lds, const bf16_t* Qm, const bf16_t* Km, const bf16_t* VT, const bf16_t* GBm, bf16_t* YB, int b, int hp, int qb) {
;     ...
;                 const float t1 = __shfl(run, (lane + 16) & 63), t2 = __shfl(run, (lane + 32) & 63), t3 = __shfl(run, (lane + 48) & 63);
;                 Gs[c] = (fq < 3 ? t1 : 1.f) * (fq < 2 ? t2 : 1.f) * (fq < 1 ? t3 : 1.f);
;                 Tt[c] = (run * t1) * (t2 * t3);
;             }
;             bf16x8 pf[2];
; #pragma unroll
;             for (int c = 0; c < 2; ++c) {
;                 const float basec = Rs * Gs[c] * (c == 0 ? Tt[1] : 1.f);
;                 float w[8];
; #pragma unroll
;                 for (int i = 0; i < 8; ++i) w[i] = be[c][i] * (suf[c][i] * basec);
;                 u32x4 pw; pw.x = cvt_pk_bf16(w[0], w[1]); pw.y = cvt_pk_bf16(w[2], w[3]); pw.z = cvt_pk_bf16(w[4], w[5]); pw.w = cvt_pk_bf16(w[6], w[7]);
;                 pf[c] = __builtin_bit_cast(bf16x8, pw);
;             }
;             Rs *= Tt[0] * Tt[1];
; #pragma unroll
;             for (int db = 0; db < 8; ++db)
; #pragma unroll
;                 for (int c = 0; c < 2; ++c) {
;                     const bf16x8 a = *(const LAS bf16x8*)(VL + (db * 16 + fr) * 144 + (32 * c + 8 * fq) * 2);
;                     o[db] = __builtin_amdgcn_mfma_f32_16x16x32_bf16(a, pf[c], o[db], 0, 0, 0);
;                 }
	v_cndmask_b32_e64 v120, v138, 1.0, s[0:1]
	v_mul_f32_e32 v121, v140, v159
	v_mul_f32_e32 v97, v120, v97
	ds_bpermute_b32 v120, v135, v121
	ds_bpermute_b32 v123, v118, v121
	ds_bpermute_b32 v122, v119, v121
	s_waitcnt lgkmcnt(3)
	v_cndmask_b32_e64 v124, 1.0, v139, s[4:5]
	v_mul_f32_e32 v124, v97, v124
	s_waitcnt lgkmcnt(2)
	v_cndmask_b32_e64 v97, 1.0, v120, s[10:11]
	s_waitcnt lgkmcnt(1)
	v_cndmask_b32_e64 v125, v123, 1.0, s[0:1]
	v_mul_f32_e32 v97, v125, v97
	s_waitcnt lgkmcnt(0)
	v_cndmask_b32_e64 v125, 1.0, v122, s[4:5]
	v_mul_f32_e32 v120, v120, v122
	v_mul_f32_e32 v121, v121, v123
	v_mul_f32_e32 v135, v97, v125
	v_mul_f32_e32 v140, v96, v124
	v_mul_f32_e32 v141, v120, v121
	v_mul_f32_e32 v97, v140, v141
	v_mul_f32_e32 v228, v103, v97
	v_mul_f32_e32 v229, v157, v97
	v_mul_f32_e32 v230, v156, v97
	v_mul_f32_e32 v231, v155, v97
	v_mul_f32_e32 v232, v154, v97
	v_mul_f32_e32 v233, v153, v97
	v_mul_f32_e32 v234, v147, v97
	v_mul_f32_e32 v101, v101, v228
	v_mul_f32_e32 v103, v142, v228
	v_mul_f32_e32 v121, v143, v229
	v_mul_f32_e32 v122, v144, v230
	v_mul_f32_e32 v123, v145, v231
	v_mul_f32_e32 v124, v146, v232
	v_mul_f32_e32 v125, v126, v233
	v_mul_f32_e32 v97, v127, v234
	v_cvt_pk_bf16_f32 v120, v101, v103
	v_cvt_pk_bf16_f32 v121, v121, v122
	v_cvt_pk_bf16_f32 v122, v123, v124
	v_cvt_pk_bf16_f32 v123, v125, v97
	v_mul_f32_e32 v97, v96, v135
	v_mul_f32_e32 v228, v97, v159
	v_mul_f32_e32 v229, v97, v158
	v_mul_f32_e32 v230, v97, v148
	v_mul_f32_e32 v231, v97, v149
	v_mul_f32_e32 v232, v97, v150
	v_mul_f32_e32 v233, v97, v152
	v_mul_f32_e32 v234, v151, v97
	v_mul_f32_e32 v101, v128, v228
	v_mul_f32_e32 v103, v129, v228
	v_mul_f32_e32 v125, v130, v229
	v_mul_f32_e32 v126, v131, v230
	v_mul_f32_e32 v127, v132, v231
	v_mul_f32_e32 v128, v133, v232
	v_mul_f32_e32 v129, v134, v233
	v_mul_f32_e32 v97, v99, v234
	v_cvt_pk_bf16_f32 v124, v101, v103
	v_cvt_pk_bf16_f32 v125, v125, v126
	v_cvt_pk_bf16_f32 v126, v127, v128
	v_cvt_pk_bf16_f32 v127, v129, v97
	ds_read_b128 v[128:131], v117 offset:17408
	ds_read_b128 v[132:135], v117 offset:17472
	s_waitcnt lgkmcnt(1)
	v_mfma_f32_16x16x32_bf16 v[60:63], v[128:131], v[120:123], v[60:63]
	ds_read_b128 v[128:131], v117 offset:19712
	s_waitcnt lgkmcnt(1)
	v_mfma_f32_16x16x32_bf16 v[60:63], v[132:135], v[124:127], v[60:63]
	ds_read_b128 v[132:135], v117 offset:19776
	s_waitcnt lgkmcnt(1)
	v_mfma_f32_16x16x32_bf16 v[72:75], v[128:131], v[120:123], v[72:75]
	ds_read_b128 v[128:131], v117 offset:22016
	s_waitcnt lgkmcnt(1)
	v_mfma_f32_16x16x32_bf16 v[72:75], v[132:135], v[124:127], v[72:75]
	ds_read_b128 v[132:135], v117 offset:22080
	s_waitcnt lgkmcnt(1)
	v_mfma_f32_16x16x32_bf16 v[56:59], v[128:131], v[120:123], v[56:59]
	ds_read_b128 v[128:131], v117 offset:24320
	s_waitcnt lgkmcnt(1)
	v_mfma_f32_16x16x32_bf16 v[56:59], v[132:135], v[124:127], v[56:59]
	ds_read_b128 v[132:135], v117 offset:24384
	s_waitcnt lgkmcnt(1)
	v_mfma_f32_16x16x32_bf16 v[44:47], v[128:131], v[120:123], v[44:47]
	ds_read_b128 v[128:131], v117 offset:26624
	s_waitcnt lgkmcnt(1)
	v_mfma_f32_16x16x32_bf16 v[44:47], v[132:135], v[124:127], v[44:47]
	ds_read_b128 v[132:135], v117 offset:26688
	s_waitcnt lgkmcnt(1)
	v_mfma_f32_16x16x32_bf16 v[32:35], v[128:131], v[120:123], v[32:35]
	ds_read_b128 v[128:131], v117 offset:28928
	s_waitcnt lgkmcnt(1)
	v_mfma_f32_16x16x32_bf16 v[32:35], v[132:135], v[124:127], v[32:35]
	ds_read_b128 v[132:135], v117 offset:28992
	s_waitcnt lgkmcnt(1)
	v_mfma_f32_16x16x32_bf16 v[24:27], v[128:131], v[120:123], v[24:27]
	ds_read_b128 v[128:131], v117 offset:31232
	s_waitcnt lgkmcnt(1)
	v_mfma_f32_16x16x32_bf16 v[24:27], v[132:135], v[124:127], v[24:27]
	ds_read_b128 v[132:135], v117 offset:31296
	s_waitcnt lgkmcnt(1)
	v_mfma_f32_16x16x32_bf16 v[20:23], v[128:131], v[120:123], v[20:23]
	ds_read_b128 v[128:131], v117 offset:33536
	s_waitcnt lgkmcnt(1)
	v_mfma_f32_16x16x32_bf16 v[20:23], v[132:135], v[124:127], v[20:23]
	ds_read_b128 v[132:135], v117 offset:33600
	s_waitcnt lgkmcnt(1)
	v_mfma_f32_16x16x32_bf16 v[16:19], v[128:131], v[120:123], v[16:19]
	v_mul_f32_e64 v120, v136, v138
	v_mul_f32_e64 v121, v137, v139
	v_mul_f32_e32 v97, v120, v121
	s_waitcnt lgkmcnt(0)
	v_mfma_f32_16x16x32_bf16 v[16:19], v[132:135], v[124:127], v[16:19]
	v_mul_f32_e32 v97, v97, v141
	v_mul_f32_e32 v96, v96, v97
